# P1 tile order: within each step of 32 concurrent tiles per XCD, workgroup positions rotated per step so every workgroup meets a similar mix of epilogue kinds
# speedup vs baseline: 1.0087x; 1.0056x over previous
.LBB0_90:
	s_bfe_u32 s2, s74, 0x20001
	s_mulk_i32 s2, 0x44
	s_lshl_b32 s3, s72, 1
	s_add_i32 s2, s2, s3
	s_and_b32 s3, s74, 1
	s_add_i32 s2, s2, s3
	s_lshr_b32 s3, s2, 5
	s_mov_b32 s12, 0x452c0
	s_mov_b32 s13, 0x71250
	s_cmp_gt_u32 s3, 3
	s_cselect_b32 s12, s13, s12
	s_and_b32 s3, s3, 3
	s_mul_i32 s3, s3, 5
	s_lshr_b32 s12, s12, s3
	s_and_b32 s12, s12, 31
	s_add_i32 s12, s2, s12
	s_and_b32 s12, s12, 31
	s_and_b32 s3, s2, -32
	s_or_b32 s12, s12, s3
	s_cmp_lt_u32 s2, 0x100
	s_cselect_b32 s2, s12, s2
	s_and_b32 s74, s74, -8
	s_mul_i32 s3, s2, 0xf1
	s_lshr_b32 s3, s3, 14
	s_lshl_b32 s72, s3, 1
	s_add_i32 s74, s74, s72
	s_mulk_i32 s3, 0x44
	s_sub_i32 s2, s2, s3
	s_lshr_b32 s72, s2, 1
	s_and_b32 s2, s2, 1
	s_add_i32 s74, s74, s2
	s_add_u32 s2, s80, 0x2000000
	s_addc_u32 s3, s81, 0
	v_writelane_b32 v254, s2, 20
	v_lshrrev_b32_e32 v246, 1, v0
	v_lshrrev_b32_e32 v239, 6, v0
	v_writelane_b32 v254, s3, 21
	v_writelane_b32 v254, s65, 22
	v_writelane_b32 v254, s63, 23
	v_writelane_b32 v254, s60, 24
	v_and_b32_e32 v2, 32, v0
	v_bfe_u32 v199, v0, 2, 4
	v_writelane_b32 v254, s61, 25
	v_writelane_b32 v254, s66, 26
	v_and_b32_e32 v203, 24, v246
	v_bfe_u32 v228, v0, 2, 2
	v_writelane_b32 v254, s67, 27
	v_writelane_b32 v254, s62, 28
	v_writelane_b32 v254, s56, 29
	v_lshlrev_b32_e32 v3, 3, v239
	v_lshrrev_b32_e32 v245, 5, v0
	v_or_b32_e32 v233, 0x2000, v230
	s_andn2_b64 vcc, exec, s[0:1]
	v_writelane_b32 v254, s57, 30
	s_mov_b32 s0, s58
	v_bitop3_b32 v232, v230, v2, 48 bitop3:0x6c
	v_or_b32_e32 v2, v203, v228
	v_and_or_b32 v229, v3, 48, v199
	v_or_b32_e32 v3, v245, v3
	v_lshrrev_b32_e32 v242, 10, v233
	v_writelane_b32 v254, s0, 31
	v_and_or_b32 v240, v3, 36, v2
	v_lshlrev_b32_e32 v3, 3, v242
	s_movk_i32 s2, 0x70
	v_writelane_b32 v254, s1, 32
	v_and_or_b32 v243, v3, s2, v199
	v_or_b32_e32 v3, v3, v245
	s_movk_i32 s2, 0x64
	v_writelane_b32 v254, s64, 33
	v_and_or_b32 v241, v3, s2, v2
	v_bfe_u32 v226, v0, 4, 2
	v_lshlrev_b32_e32 v2, 6, v0
	v_writelane_b32 v254, s54, 34
	v_lshlrev_b32_e32 v227, 4, v226
	v_and_b32_e32 v235, 0x3c0, v2
	v_and_b32_e32 v236, 32, v198
	v_writelane_b32 v254, s52, 35
	v_lshlrev_b32_e32 v237, 11, v229
	v_lshlrev_b32_e32 v238, 11, v243
	v_and_b32_e32 v231, 15, v0
	v_bitop3_b32 v201, v227, v236, v235 bitop3:0x36
	v_and_b32_e32 v234, 64, v0
	v_writelane_b32 v254, s53, 36
	s_cbranch_vccnz .LBB0_171
	s_lshr_b32 s2, s14, 6
	s_ashr_i32 s75, s74, 31
	s_lshr_b32 s6, s14, 8
	s_lshl_b32 s3, s2, 10
	s_lshl_b64 s[8:9], s[74:75], 19
	s_cmp_gt_i32 s33, 0
	s_cselect_b32 s5, 0x40000, 0
	s_ashr_i32 s73, s72, 31
	s_lshl_b64 s[0:1], s[72:73], 19
	s_add_u32 s0, s10, s0
	s_addc_u32 s1, s11, s1
	s_add_i32 s61, s3, 0
	v_or_b32_e32 v2, v232, v234
	s_add_i32 s73, s61, 0x10000
	s_add_i32 s75, s61, 0x12000
	v_or_b32_e32 v206, v237, v2
	v_lshl_or_b32 v208, v240, 11, v2
	v_lshlrev_b32_e32 v2, 6, v242
	s_add_u32 s3, s80, s8
	v_and_b32_e32 v3, 64, v2
	s_addc_u32 s7, s81, s9
	v_or_b32_e32 v2, v3, v232
	s_mov_b32 m0, s73
	s_add_u32 s8, s0, 0x40000
	v_lshl_or_b32 v212, v241, 11, v2
	global_load_lds_dwordx4 v208, s[0:1]
	s_mov_b32 m0, s75
	s_addc_u32 s9, s1, 0
	s_add_i32 s92, s61, 0x14000
	s_add_i32 s93, s61, 0x16000
	global_load_lds_dwordx4 v212, s[0:1]
	s_mov_b32 m0, s92
	s_add_u32 s76, s3, s5
	global_load_lds_dwordx4 v208, s[8:9]
	s_mov_b32 m0, s93
	s_addc_u32 s77, s7, 0
	s_add_i32 s94, s61, 0x2000
	global_load_lds_dwordx4 v212, s[8:9]
	s_mov_b32 m0, s61
	s_add_u32 s8, s76, 0x40000
	v_or_b32_e32 v210, v238, v2
	global_load_lds_dwordx4 v206, s[76:77]
	s_mov_b32 m0, s94
	s_addc_u32 s9, s77, 0
	s_add_i32 s95, s61, 0x4000
	global_load_lds_dwordx4 v210, s[76:77]
	s_mov_b32 m0, s95
	s_add_i32 s96, s61, 0x6000
	global_load_lds_dwordx4 v206, s[8:9]
	s_mov_b32 m0, s96
	v_mov_b32_e32 v2, 0
	global_load_lds_dwordx4 v210, s[8:9]
	v_mov_b32_e32 v209, v2
	v_mov_b32_e32 v213, v2
	v_mov_b32_e32 v207, v2
	v_mov_b32_e32 v211, v2
	s_cmp_eq_u32 s6, 1
	s_mov_b32 s5, 0
	s_mov_b32 s48, 0x10000
	v_lshl_add_u64 v[8:9], s[0:1], 0, v[208:209]
	v_lshl_add_u64 v[6:7], s[0:1], 0, v[212:213]
	v_lshl_add_u64 v[10:11], s[76:77], 0, v[206:207]
	v_lshl_add_u64 v[4:5], s[76:77], 0, v[210:211]
	s_cselect_b64 s[8:9], -1, 0
	s_cmp_lg_u32 s6, 1
	s_cbranch_scc1 .LBB0_93
	s_barrier

.LBB0_104:
	s_bfe_u32 s2, s64, 0x20001
	s_mulk_i32 s2, 0x44
	s_lshl_b32 s3, s62, 1
	s_add_i32 s2, s2, s3
	s_and_b32 s3, s64, 1
	s_add_i32 s2, s2, s3
	s_lshr_b32 s3, s2, 5
	s_mov_b32 s12, 0x452c0
	s_mov_b32 s13, 0x71250
	s_cmp_gt_u32 s3, 3
	s_cselect_b32 s12, s13, s12
	s_and_b32 s3, s3, 3
	s_mul_i32 s3, s3, 5
	s_lshr_b32 s12, s12, s3
	s_and_b32 s12, s12, 31
	s_add_i32 s12, s2, s12
	s_and_b32 s12, s12, 31
	s_and_b32 s3, s2, -32
	s_or_b32 s12, s12, s3
	s_cmp_lt_u32 s2, 0x100
	s_cselect_b32 s2, s12, s2
	s_and_b32 s64, s64, -8
	s_mul_i32 s3, s2, 0xf1
	s_lshr_b32 s3, s3, 14
	s_lshl_b32 s62, s3, 1
	s_add_i32 s64, s64, s62
	s_mulk_i32 s3, 0x44
	s_sub_i32 s2, s2, s3
	s_lshr_b32 s62, s2, 1
	s_and_b32 s2, s2, 1
	s_add_i32 s64, s64, s2
	s_ashr_i32 s65, s64, 31
	s_lshl_b64 s[2:3], s[64:65], 19
	s_add_u32 s2, s80, s2
	s_addc_u32 s3, s81, s3
	s_cmp_gt_i32 s42, 0
	s_cselect_b32 s4, 0x40000, 0
	s_add_u32 s68, s2, s4
	s_addc_u32 s69, s3, 0
	s_and_b64 s[2:3], s[66:67], exec
	s_cselect_b32 s4, s69, s77
	s_cselect_b32 s43, s68, s76
	s_ashr_i32 s63, s62, 31
	s_lshl_b64 s[2:3], s[62:63], 19
	s_add_u32 s70, s10, s2
	s_addc_u32 s71, s11, s3
	s_and_b64 s[2:3], s[66:67], exec
	s_cselect_b32 s63, s71, s1
	s_cselect_b32 s65, s70, s0
	s_cmp_lt_i32 s33, 0
	v_mov_b32_e32 v4, v2
	v_mov_b32_e32 v5, v2
	s_cselect_b64 s[86:87], -1, 0
	s_add_u32 s36, s0, 0x100
	v_mov_b32_e32 v3, v2
	v_mov_b64_e32 v[70:71], v[4:5]
	v_mov_b64_e32 v[72:73], v[4:5]
	v_mov_b64_e32 v[74:75], v[4:5]
	v_mov_b64_e32 v[76:77], v[4:5]
	v_mov_b64_e32 v[78:79], v[4:5]
	v_mov_b64_e32 v[80:81], v[4:5]
	v_mov_b64_e32 v[82:83], v[4:5]
	v_mov_b64_e32 v[84:85], v[4:5]
	v_mov_b64_e32 v[86:87], v[4:5]
	v_mov_b64_e32 v[88:89], v[4:5]
	v_mov_b64_e32 v[90:91], v[4:5]
	v_mov_b64_e32 v[92:93], v[4:5]
	v_mov_b64_e32 v[94:95], v[4:5]
	v_mov_b64_e32 v[96:97], v[4:5]
	v_mov_b64_e32 v[98:99], v[4:5]
	v_mov_b64_e32 v[100:101], v[4:5]
	v_mov_b64_e32 v[102:103], v[4:5]
	v_mov_b64_e32 v[104:105], v[4:5]
	v_mov_b64_e32 v[106:107], v[4:5]
	v_mov_b64_e32 v[108:109], v[4:5]
	v_mov_b64_e32 v[110:111], v[4:5]
	v_mov_b64_e32 v[112:113], v[4:5]
	v_mov_b64_e32 v[114:115], v[4:5]
	v_mov_b64_e32 v[116:117], v[4:5]
	v_mov_b64_e32 v[118:119], v[4:5]
	v_mov_b64_e32 v[120:121], v[4:5]
	v_mov_b64_e32 v[122:123], v[4:5]
	v_mov_b64_e32 v[124:125], v[4:5]
	v_mov_b64_e32 v[126:127], v[4:5]
	v_mov_b64_e32 v[128:129], v[4:5]
	v_mov_b64_e32 v[130:131], v[4:5]
	v_mov_b64_e32 v[132:133], v[4:5]
	v_mov_b64_e32 v[24:25], v[4:5]
	v_mov_b64_e32 v[56:57], v[4:5]
	v_mov_b64_e32 v[28:29], v[4:5]
	v_mov_b64_e32 v[60:61], v[4:5]
	v_mov_b64_e32 v[36:37], v[4:5]
	v_mov_b64_e32 v[68:69], v[4:5]
	v_mov_b64_e32 v[32:33], v[4:5]
	v_mov_b64_e32 v[64:65], v[4:5]
	v_mov_b64_e32 v[12:13], v[4:5]
	v_mov_b64_e32 v[44:45], v[4:5]
	v_mov_b64_e32 v[16:17], v[4:5]
	v_mov_b64_e32 v[48:49], v[4:5]
	v_mov_b64_e32 v[20:21], v[4:5]
	v_mov_b64_e32 v[52:53], v[4:5]
	v_mov_b64_e32 v[8:9], v[4:5]
	v_mov_b64_e32 v[40:41], v[4:5]
	s_addc_u32 s44, s1, 0
	s_mov_b32 s45, -2
	v_mov_b64_e32 v[22:23], v[2:3]
	v_mov_b64_e32 v[54:55], v[2:3]
	v_mov_b64_e32 v[26:27], v[2:3]
	v_mov_b64_e32 v[58:59], v[2:3]
	v_mov_b64_e32 v[34:35], v[2:3]
	v_mov_b64_e32 v[66:67], v[2:3]
	v_mov_b64_e32 v[30:31], v[2:3]
	v_mov_b64_e32 v[62:63], v[2:3]
	v_mov_b64_e32 v[10:11], v[2:3]
	v_mov_b64_e32 v[42:43], v[2:3]
	v_mov_b64_e32 v[14:15], v[2:3]
	v_mov_b64_e32 v[46:47], v[2:3]
	v_mov_b64_e32 v[18:19], v[2:3]
	v_mov_b64_e32 v[50:51], v[2:3]
	v_mov_b64_e32 v[6:7], v[2:3]
	v_mov_b64_e32 v[38:39], v[2:3]
	s_and_b64 vcc, exec, s[86:87]
	s_cbranch_vccnz .LBB0_107
	s_add_u32 s2, s0, 0x100
	s_addc_u32 s3, s1, 0
	s_add_u32 s84, s76, 0x100
	s_addc_u32 s85, s77, 0
	v_add_u32_e32 v220, 0x18000, v247
	v_add_u32_e32 v221, 0x1c000, v247
	v_add_u32_e32 v222, 0xc000, v247
	v_add_u32_e32 v223, 0x20000, v247
	s_mov_b32 s45, 0
	s_waitcnt vmcnt(0)
	s_and_b64 vcc, exec, s[14:15]
	s_cbranch_vccz .Lhu_y
